# XCD-local grid barriers for seams after phases 2..27 (leader skips L2 writeback + cross-XCD rendezvous), conv/pool rows remapped XCD-local, BIG/ORAW relocated into per-XCD slabs
# speedup vs baseline: 1.0085x; 1.0085x over previous
; __global__ void __launch_bounds__(NWAVES * 64, 2) trunk_fwd(Args args) {
;     ...
;         int kind, l; decode_phase(ph, kind, l); const int li = l >> 1;
;         int tid_ = threadIdx.x, G_ = gridDim.x, bid_ = blockIdx.x; asm volatile("" : "+v"(tid_), "+s"(G_), "+s"(bid_));
;         const int tid = tid_, lane = tid & 63, wid = __builtin_amdgcn_readfirstlane(tid >> 6), G = G_, bid = bid_, gw = bid * NWAVES + wid, NGW = G * NWAVES;
;         const __attribute__((address_space(4))) Args* ap = (const __attribute__((address_space(4))) Args*)__builtin_amdgcn_kernarg_segment_ptr();
;         asm volatile("" : "+s"(ap));
;     ...
;         unsigned char* ws = ap->ws;
;         float* out = ap->out;
;         float* TAB = (float*)(ws + WS_SMALL); float* LAM = (float*)(ws + WS_SMALL + 16384);
;         bf16* WIN = (bf16*)(ws + WS_WIN); bf16* WOUT = (bf16*)(ws + WS_WOUT); bf16* CIN = (bf16*)(ws + WS_CIN); bf16* COUT = (bf16*)(ws + WS_COUT);
;         bf16* WQ = (bf16*)(ws + WS_WQ); bf16* WK = (bf16*)(ws + WS_WK); bf16* WV = (bf16*)(ws + WS_WV); bf16* WO = (bf16*)(ws + WS_WO); bf16* W1 = (bf16*)(ws + WS_W1); bf16* W2 = (bf16*)(ws + WS_W2);
;         bf16* MEMN = (bf16*)(ws + WS_MEMN); bf16* KB = (bf16*)(ws + WS_KB); bf16* VT = (bf16*)(ws + WS_VT); float* SSQ = (float*)(ws + WS_SSQ);
;         bf16* HB = (bf16*)(ws + WS_HB); bf16* MIX = (bf16*)(ws + WS_MIX); bf16* BIG = (bf16*)(ws + WS_BIG); bf16* ORAW = (bf16*)(ws + WS_ORAW);
.LBB0_197:
	v_writelane_b32 v255, s3, 15
	v_writelane_b32 v255, s8, 16
	v_mov_b32_e32 v250, v206
	s_mov_b64 s[74:75], -1
	v_writelane_b32 v255, s9, 17
	v_writelane_b32 v255, s66, 18
	s_mov_b64 s[8:9], 0
	s_mov_b64 s[70:71], 0
	v_writelane_b32 v255, s67, 19
	s_mov_b64 s[68:69], 0
	v_readlane_b32 s0, v255, 0
	v_readlane_b32 s4, v255, 1
	v_readlane_b32 s62, v255, 3
	s_mov_b32 s48, s0
	s_mov_b32 s0, s4
	v_readlane_b32 s63, v255, 4
	s_load_dwordx4 s[16:19], s[62:63], 0xc8
	v_readfirstlane_b32 s3, v250
	s_ashr_i32 s3, s3, 6
	v_readlane_b32 s5, v255, 2
	v_mov_b32_e32 v0, s3
	s_waitcnt lgkmcnt(0)
	s_add_u32 s56, s18, 0xc600000
	s_addc_u32 s57, s19, 0
	s_add_u32 s58, s18, 0xca00000
	v_lshl_add_u32 v0, s48, 3, v0
	s_addc_u32 s59, s19, 0
	v_readfirstlane_b32 s60, v0
	v_lshlrev_b32_e64 v0, 3, s0
	s_add_u32 s50, s18, 0x14a00000
	v_writelane_b32 v255, s3, 20
	v_readfirstlane_b32 s3, v0
	s_addc_u32 s51, s19, 0
	s_add_u32 s52, s18, 0x1ca00000
	v_writelane_b32 v255, s3, 21
	s_addc_u32 s53, s19, 0
	v_readlane_b32 s3, v255, 15
	v_writelane_b32 v255, s8, 22
	s_and_b32 s4, s48, 7
	s_lshl_b32 s5, s4, 25
	s_mul_i32 s4, s4, 0x3000000
	s_cmp_eq_u32 s3, 6
	s_cselect_b32 s4, s4, 0
	s_cmp_eq_u32 s3, 1
	s_cselect_b32 s4, s5, s4
	s_cmp_eq_u32 s3, 2
	s_cselect_b32 s4, s5, s4
	s_cmp_eq_u32 s3, 4
	s_cselect_b32 s4, s5, s4
	s_add_u32 s52, s52, s4
	s_addc_u32 s53, s53, 0
	s_cmp_lt_i32 s3, 6
	s_nop 0
	v_writelane_b32 v255, s9, 23
	s_mov_b64 s[8:9], 0
	s_cbranch_scc1 .LBB0_289
	v_readlane_b32 s3, v255, 15
	s_mov_b64 s[4:5], -1
	s_cmp_gt_i32 s3, 8
	s_cbranch_scc0 .LBB0_282
	v_readlane_b32 s3, v255, 15
	s_cmp_gt_i32 s3, 9
	s_cbranch_scc0 .LBB0_202
	s_mov_b64 s[4:5], 0
	s_mov_b64 s[68:69], -1
	s_cmp_eq_u32 s3, 10
	s_cbranch_scc0 .LBB0_202
	s_mov_b64 s[8:9], -1
	s_mov_b64 s[68:69], 0

; __global__ void __launch_bounds__(NWAVES * 64, 2) trunk_fwd(Args args) {
;     ...
;             for (int task = gw; task < (M / 32) * 2; task += NGW) {
;                 const int row0 = (task >> 1) * 32, t0 = row0 & (SEQ - 1), ch = (task & 1) * 512 + lane * 8;
;                 const float* cw = ARGIN(I_CW) + (size_t)li * 3 * 1024 + ch;
;                 float w0[8], w1[8], w2[8];
; #pragma unroll
;                 for (int e = 0; e < 8; ++e) { w0[e] = cw[e]; w1[e] = cw[1024 + e]; w2[e] = cw[2048 + e]; }
;                 const bf16* pp = BIG + (size_t)row0 * 2048 + ch; bf16* op = MIX + (size_t)row0 * 1024 + ch;
.LBB0_343:
	v_readlane_b32 s42, v255, 22
	v_and_b32_e32 v216, 63, v250
	s_and_b64 vcc, exec, s[74:75]
	v_readlane_b32 s28, v255, 21
	v_readlane_b32 s43, v255, 23
	s_cbranch_vccz .LBB0_352
	s_cmpk_gt_i32 s60, 0xfff
	v_readlane_b32 s27, v255, 26
	v_readlane_b32 s26, v255, 27
	s_cbranch_scc1 .LBB0_352
	s_load_dwordx2 s[4:5], s[62:63], 0x90
	v_readlane_b32 s6, v255, 24
	v_readlane_b32 s7, v255, 25
	s_mul_hi_i32 s3, s6, 0x3000
	s_mulk_i32 s6, 0x3000
	s_waitcnt lgkmcnt(0)
	s_add_u32 s4, s4, s6
	v_readlane_b32 s7, v255, 20
	s_addc_u32 s5, s5, s3
	s_and_b32 s20, s48, 7
	s_lshl_b32 s20, s20, 9
	s_lshr_b32 s6, s48, 3
	s_lshl_b32 s6, s6, 3
	s_add_i32 s20, s20, s6
	s_add_i32 s20, s20, s7
	s_lshl_b32 s3, s20, 9
	v_lshlrev_b32_e32 v132, 3, v216
	s_mov_b32 s12, 0x20000
	s_lshl_b32 s14, s20, 4
	s_movk_i32 s15, 0x1000

; __device__ __forceinline__ float bf_lo(unsigned w) { return __uint_as_float(w << 16); }
; __device__ __forceinline__ float bf_hi(unsigned w) { return __uint_as_float(w & 0xffff0000u); }
; __device__ __forceinline__ unsigned pk2(float lo, float hi) { return pg8::cvt_pk_bf16(lo, hi); }
; __global__ void __launch_bounds__(NWAVES * 64, 2) trunk_fwd(Args args) {
;     ...
;                 const bf16* pp = BIG + (size_t)row0 * 2048 + ch; bf16* op = MIX + (size_t)row0 * 1024 + ch;
;                 float z1[8], z2[8];
; #pragma unroll
;                 for (int e = 0; e < 8; ++e) { z1[e] = 0.f; z2[e] = 0.f; }
;                 if (t0 > 0) {
;                     const v4u q1 = *(const v4u*)(pp - 2048 + 1024), q2 = *(const v4u*)(pp - 2 * 2048 + 1024);
;                     z1[0] = bf_lo(q1.x); z1[1] = bf_hi(q1.x); z1[2] = bf_lo(q1.y); z1[3] = bf_hi(q1.y); z1[4] = bf_lo(q1.z); z1[5] = bf_hi(q1.z); z1[6] = bf_lo(q1.w); z1[7] = bf_hi(q1.w);
;                     z2[0] = bf_lo(q2.x); z2[1] = bf_hi(q2.x); z2[2] = bf_lo(q2.y); z2[3] = bf_hi(q2.y); z2[4] = bf_lo(q2.z); z2[5] = bf_hi(q2.z); z2[6] = bf_lo(q2.w); z2[7] = bf_hi(q2.w);
;                 }
;                 for (int i0 = 0; i0 < 32; i0 += 8) {
;                     v4u bqq[8], zqq[8];
; #pragma unroll
;                     for (int k = 0; k < 8; ++k) { bqq[k] = __builtin_nontemporal_load((const v4u*)(pp + (size_t)(i0 + k) * 2048)); zqq[k] = __builtin_nontemporal_load((const v4u*)(pp + (size_t)(i0 + k) * 2048 + 1024)); }
; #pragma unroll
;                     for (int k = 0; k < 8; ++k) { const int i = i0 + k; const v4u bq = bqq[k], zq = zqq[k];
;                     const float bb[8] = {bf_lo(bq.x), bf_hi(bq.x), bf_lo(bq.y), bf_hi(bq.y), bf_lo(bq.z), bf_hi(bq.z), bf_lo(bq.w), bf_hi(bq.w)};
;                     const float z[8] = {bf_lo(zq.x), bf_hi(zq.x), bf_lo(zq.y), bf_hi(zq.y), bf_lo(zq.z), bf_hi(zq.z), bf_lo(zq.w), bf_hi(zq.w)};
;                     float y[8];
; #pragma unroll
;                     for (int e = 0; e < 8; ++e) { y[e] = bb[e] * (z2[e] * w0[e] + z1[e] * w1[e] + z[e] * w2[e]); z2[e] = z1[e]; z1[e] = z[e]; }
;                     v4u r; r.x = pk2(y[0], y[1]); r.y = pk2(y[2], y[3]); r.z = pk2(y[4], y[5]); r.w = pk2(y[6], y[7]);
;                     *(v4u*)(op + (size_t)i * 1024) = r; }
;                 }
.LBB0_349:
	s_lshl_b32 s6, s3, 1
	s_and_b32 s8, s14, 0xffffffe0
	s_and_b32 s6, s6, 0x400
	s_ashr_i32 s9, s8, 31
	v_lshl_or_b32 v0, v132, 1, s6
	s_lshl_b64 s[6:7], s[8:9], 12
	s_add_u32 s6, s18, s6
	s_addc_u32 s7, s19, s7
	s_and_b32 s26, s48, 7
	s_lshl_b32 s26, s26, 25
	s_add_u32 s6, s6, s26
	s_addc_u32 s7, s7, 0
	s_lshl_b64 s[8:9], s[8:9], 11
	s_add_u32 s8, s18, s8
	s_waitcnt vmcnt(1)
	v_mov_b32_e32 v99, v18
	v_mov_b32_e32 v101, v20
	s_waitcnt vmcnt(0)
	v_mov_b32_e32 v103, v22
	v_mov_b32_e32 v105, v24
	s_addc_u32 s9, s19, s9
	v_mov_b32_e32 v98, v6
	v_mov_b32_e32 v18, v7
	v_mov_b32_e32 v100, v8
	v_mov_b32_e32 v20, v9
	v_mov_b32_e32 v102, v2
	v_mov_b32_e32 v22, v3
	v_mov_b32_e32 v104, v4
	v_mov_b32_e32 v24, v5
	v_mov_b32_e32 v106, v10
	v_mov_b32_e32 v107, v99
	v_mov_b32_e32 v108, v11
	v_mov_b32_e32 v109, v19
	v_mov_b32_e32 v110, v12
	v_mov_b32_e32 v111, v101
	v_mov_b32_e32 v112, v13
	v_mov_b32_e32 v113, v21
	v_mov_b32_e32 v114, v14
	v_mov_b32_e32 v115, v103
	v_mov_b32_e32 v116, v15
	v_mov_b32_e32 v117, v23
	v_mov_b32_e32 v118, v16
	v_mov_b32_e32 v119, v105
	v_mov_b32_e32 v120, v17
	v_mov_b32_e32 v121, v25
	s_mov_b32 s26, -8
.LBB0_350:
	s_nop 0
	v_lshl_add_u64 v[26:27], s[6:7], 0, v[0:1]
	s_mov_b32 s27, 0x1ca00000
	v_add_co_u32_e32 v28, vcc, s27, v26
	s_mov_b32 s27, 0x1ca01000
	s_nop 0
	v_addc_co_u32_e32 v29, vcc, 0, v27, vcc
	v_add_co_u32_e32 v30, vcc, s27, v26
	s_mov_b32 s27, 0x1ca02000
	s_nop 0
	v_addc_co_u32_e32 v31, vcc, 0, v27, vcc
	global_load_dwordx4 v[134:137], v[30:31], off offset:-4096 nt
	global_load_dwordx4 v[74:77], v[28:29], off offset:2048 nt
	global_load_dwordx4 v[138:141], v[30:31], off nt
	global_load_dwordx4 v[78:81], v[30:31], off offset:2048 nt
	v_add_co_u32_e32 v28, vcc, s27, v26
	s_mov_b32 s27, 0x1ca03000
	s_nop 0
	v_addc_co_u32_e32 v29, vcc, 0, v27, vcc
	v_add_co_u32_e32 v30, vcc, s27, v26
	s_mov_b32 s27, 0x1ca04000
	s_nop 0
	v_addc_co_u32_e32 v31, vcc, 0, v27, vcc
	global_load_dwordx4 v[70:73], v[30:31], off offset:-4096 nt
	global_load_dwordx4 v[58:61], v[28:29], off offset:2048 nt
	global_load_dwordx4 v[66:69], v[30:31], off nt
	global_load_dwordx4 v[62:65], v[30:31], off offset:2048 nt
	v_add_co_u32_e32 v28, vcc, s27, v26
	s_mov_b32 s27, 0x1ca05000
	s_nop 0
	v_addc_co_u32_e32 v29, vcc, 0, v27, vcc
	v_add_co_u32_e32 v30, vcc, s27, v26
	s_mov_b32 s27, 0x1ca06000
	s_nop 0
	v_addc_co_u32_e32 v31, vcc, 0, v27, vcc
	global_load_dwordx4 v[54:57], v[30:31], off offset:-4096 nt
	global_load_dwordx4 v[42:45], v[28:29], off offset:2048 nt
	global_load_dwordx4 v[50:53], v[30:31], off nt
	global_load_dwordx4 v[46:49], v[30:31], off offset:2048 nt
	v_add_co_u32_e32 v28, vcc, s27, v26
	s_mov_b32 s27, 0x1ca07000
	s_nop 0
	v_addc_co_u32_e32 v29, vcc, 0, v27, vcc
	v_add_co_u32_e32 v30, vcc, s27, v26
	v_lshl_add_u64 v[122:123], s[8:9], 0, v[0:1]
	s_nop 0
	v_addc_co_u32_e32 v31, vcc, 0, v27, vcc
	global_load_dwordx4 v[38:41], v[30:31], off offset:-4096 nt
	s_nop 0
	global_load_dwordx4 v[26:29], v[28:29], off offset:2048 nt
	s_nop 0
	global_load_dwordx4 v[34:37], v[30:31], off nt
	s_nop 0
	global_load_dwordx4 v[30:33], v[30:31], off offset:2048 nt
	s_mov_b32 s27, 0x14a02000
	s_add_u32 s6, s6, 0x8000
	s_addc_u32 s7, s7, 0
	s_add_u32 s8, s8, 0x4000
	s_addc_u32 s9, s9, 0
	s_add_i32 s26, s26, 8
	s_cmp_gt_u32 s26, 23
	s_waitcnt vmcnt(15)
	v_lshlrev_b32_e32 v90, 16, v134
	v_and_b32_e32 v92, 0xffff0000, v134
	s_waitcnt vmcnt(14)
	v_lshlrev_b32_e32 v134, 16, v74
	v_mov_b32_e32 v131, v134
	v_pk_mul_f32 v[130:131], v[130:131], v[98:99]
	v_lshlrev_b32_e32 v94, 16, v135
	v_and_b32_e32 v96, 0xffff0000, v135
	s_waitcnt vmcnt(12)
	v_lshlrev_b32_e32 v135, 16, v78
	v_fma_f32 v129, v83, v10, v130
	v_add_f32_e32 v129, v129, v131
	v_pk_mul_f32 v[130:131], v[106:107], v[134:135]
	v_mul_f32_e32 v90, v129, v90
	v_fma_f32 v83, v83, v6, v130
	v_and_b32_e32 v130, 0xffff0000, v74
	v_mov_b32_e32 v129, v130
	v_pk_mul_f32 v[128:129], v[128:129], v[18:19]
	v_add_f32_e32 v83, v83, v131
	v_and_b32_e32 v131, 0xffff0000, v78
	v_fma_f32 v74, v85, v11, v128
	v_add_f32_e32 v74, v74, v129
	v_pk_mul_f32 v[128:129], v[108:109], v[130:131]
	v_and_b32_e32 v127, 0xffff0000, v138
	v_fma_f32 v78, v85, v7, v128
	v_mul_f32_e32 v74, v74, v92
	v_add_f32_e32 v78, v78, v129
	v_lshlrev_b32_e32 v128, 16, v75
	v_cvt_pk_bf16_f32 v74, v90, v74
	v_mul_f32_e32 v90, v78, v127
	v_mov_b32_e32 v127, v128
	v_pk_mul_f32 v[126:127], v[126:127], v[100:101]
	v_lshlrev_b32_e32 v129, 16, v79
	v_fma_f32 v78, v87, v12, v126
	v_lshlrev_b32_e32 v125, 16, v138
	v_add_f32_e32 v78, v78, v127
	v_pk_mul_f32 v[126:127], v[110:111], v[128:129]
	v_mul_f32_e32 v145, v83, v125
	v_mul_f32_e32 v83, v78, v94
	v_fma_f32 v78, v87, v8, v126
	v_lshlrev_b32_e32 v138, 16, v139
	v_add_f32_e32 v78, v78, v127
	v_mul_f32_e32 v92, v78, v138
	v_and_b32_e32 v78, 0xffff0000, v75
	v_mov_b32_e32 v125, v78
	v_pk_mul_f32 v[124:125], v[124:125], v[20:21]
	v_and_b32_e32 v79, 0xffff0000, v79
	v_fma_f32 v75, v89, v13, v124
	v_add_f32_e32 v75, v75, v125
	v_mul_f32_e32 v75, v75, v96
	v_pk_mul_f32 v[124:125], v[112:113], v[78:79]
	v_cvt_pk_bf16_f32 v75, v83, v75
	v_and_b32_e32 v139, 0xffff0000, v139
	v_fma_f32 v83, v89, v9, v124
	v_lshlrev_b32_e32 v124, 16, v76
	v_mov_b32_e32 v89, v124
	v_add_f32_e32 v83, v83, v125
	v_pk_mul_f32 v[88:89], v[88:89], v[102:103]
	v_mul_f32_e32 v94, v83, v139
	v_lshlrev_b32_e32 v125, 16, v80
	v_fma_f32 v83, v91, v14, v88
	v_add_f32_e32 v83, v83, v89
	v_pk_mul_f32 v[88:89], v[114:115], v[124:125]
	v_lshlrev_b32_e32 v143, 16, v140
	v_fma_f32 v85, v91, v2, v88
	v_and_b32_e32 v88, 0xffff0000, v76
	v_mov_b32_e32 v87, v88
	v_pk_mul_f32 v[86:87], v[86:87], v[22:23]
	v_add_f32_e32 v85, v85, v89
	v_and_b32_e32 v89, 0xffff0000, v80
; __device__ __forceinline__ float bf_lo(unsigned w) { return __uint_as_float(w << 16); }
; __device__ __forceinline__ float bf_hi(unsigned w) { return __uint_as_float(w & 0xffff0000u); }
; __device__ __forceinline__ unsigned pk2(float lo, float hi) { return pg8::cvt_pk_bf16(lo, hi); }
; __global__ void __launch_bounds__(NWAVES * 64, 2) trunk_fwd(Args args) {
;     ...
;                     for (int k = 0; k < 8; ++k) { const int i = i0 + k; const v4u bq = bqq[k], zq = zqq[k];
;                     const float bb[8] = {bf_lo(bq.x), bf_hi(bq.x), bf_lo(bq.y), bf_hi(bq.y), bf_lo(bq.z), bf_hi(bq.z), bf_lo(bq.w), bf_hi(bq.w)};
;                     const float z[8] = {bf_lo(zq.x), bf_hi(zq.x), bf_lo(zq.y), bf_hi(zq.y), bf_lo(zq.z), bf_hi(zq.z), bf_lo(zq.w), bf_hi(zq.w)};
;                     float y[8];
; #pragma unroll
;                     for (int e = 0; e < 8; ++e) { y[e] = bb[e] * (z2[e] * w0[e] + z1[e] * w1[e] + z[e] * w2[e]); z2[e] = z1[e]; z1[e] = z[e]; }
;                     v4u r; r.x = pk2(y[0], y[1]); r.y = pk2(y[2], y[3]); r.z = pk2(y[4], y[5]); r.w = pk2(y[6], y[7]);
;                     *(v4u*)(op + (size_t)i * 1024) = r; }
	v_fma_f32 v76, v93, v15, v86
	v_add_f32_e32 v76, v76, v87
	v_pk_mul_f32 v[86:87], v[116:117], v[88:89]
	v_mul_f32_e32 v91, v85, v143
	v_fma_f32 v80, v93, v3, v86
	v_lshlrev_b32_e32 v86, 16, v77
	v_mov_b32_e32 v85, v86
	v_and_b32_e32 v140, 0xffff0000, v140
	v_add_f32_e32 v80, v80, v87
	v_pk_mul_f32 v[84:85], v[84:85], v[104:105]
	v_mul_f32_e32 v93, v80, v140
	v_lshlrev_b32_e32 v87, 16, v81
	v_fma_f32 v80, v95, v16, v84
	v_lshlrev_b32_e32 v142, 16, v137
	v_add_f32_e32 v80, v80, v85
	v_pk_mul_f32 v[84:85], v[118:119], v[86:87]
	v_mul_f32_e32 v96, v80, v142
	v_fma_f32 v80, v95, v4, v84
	v_lshlrev_b32_e32 v133, 16, v136
	v_and_b32_e32 v136, 0xffff0000, v136
	v_lshlrev_b32_e32 v144, 16, v141
	v_add_f32_e32 v80, v80, v85
	v_mul_f32_e32 v83, v83, v133
	v_mul_f32_e32 v76, v76, v136
	v_mul_f32_e32 v95, v80, v144
	v_and_b32_e32 v80, 0xffff0000, v77
	v_cvt_pk_bf16_f32 v76, v83, v76
	v_mov_b32_e32 v83, v80
	v_pk_mul_f32 v[82:83], v[82:83], v[24:25]
	v_and_b32_e32 v137, 0xffff0000, v137
	v_fma_f32 v77, v97, v17, v82
	v_add_co_u32_e32 v82, vcc, s10, v122
	v_add_f32_e32 v77, v77, v83
	s_nop 0
	v_addc_co_u32_e32 v83, vcc, 0, v123, vcc
	v_add_co_u32_e32 v84, vcc, s11, v122
	v_and_b32_e32 v81, 0xffff0000, v81
	v_mul_f32_e32 v77, v77, v137
	v_addc_co_u32_e32 v85, vcc, 0, v123, vcc
	v_cvt_pk_bf16_f32 v77, v96, v77
	global_store_dwordx4 v[84:85], v[74:77], off offset:-4096
	v_and_b32_e32 v141, 0xffff0000, v141
	s_waitcnt vmcnt(10)
	v_lshlrev_b32_e32 v96, 16, v69
	v_pk_mul_f32 v[74:75], v[120:121], v[80:81]
	s_nop 0
	v_fma_f32 v74, v97, v5, v74
	v_add_f32_e32 v74, v74, v75
	v_mul_f32_e32 v77, v74, v141
	v_cvt_pk_bf16_f32 v74, v145, v90
	v_cvt_pk_bf16_f32 v75, v92, v94
	v_cvt_pk_bf16_f32 v76, v91, v93
	v_cvt_pk_bf16_f32 v77, v95, v77
	global_store_dwordx4 v[82:83], v[74:77], off offset:2048
	v_lshlrev_b32_e32 v82, 16, v72
	v_and_b32_e32 v83, 0xffff0000, v72
	v_lshlrev_b32_e32 v74, 16, v70
	v_and_b32_e32 v75, 0xffff0000, v70
	v_lshlrev_b32_e32 v70, 16, v66
	v_and_b32_e32 v72, 0xffff0000, v66
	v_lshlrev_b32_e32 v66, 16, v58
	v_lshlrev_b32_e32 v94, 16, v68
	v_and_b32_e32 v95, 0xffff0000, v68
	v_and_b32_e32 v97, 0xffff0000, v69
	v_mov_b32_e32 v68, v134
	v_mov_b32_e32 v69, v66
	v_pk_mul_f32 v[68:69], v[98:99], v[68:69]
	v_lshlrev_b32_e32 v92, 16, v67
	v_fma_f32 v68, v10, v135, v68
	v_and_b32_e32 v93, 0xffff0000, v67
	s_waitcnt vmcnt(10)
	v_lshlrev_b32_e32 v67, 16, v62
	v_add_f32_e32 v68, v68, v69
	v_lshlrev_b32_e32 v90, 16, v73
	v_and_b32_e32 v91, 0xffff0000, v73
	v_mul_f32_e32 v73, v68, v74
	v_pk_mul_f32 v[68:69], v[106:107], v[66:67]
	v_lshlrev_b32_e32 v76, 16, v71
	v_fma_f32 v68, v6, v135, v68
	v_add_f32_e32 v68, v68, v69
	v_mul_f32_e32 v126, v68, v70
	v_and_b32_e32 v70, 0xffff0000, v58
	v_mov_b32_e32 v68, v130
	v_mov_b32_e32 v69, v70
	v_pk_mul_f32 v[68:69], v[18:19], v[68:69]
	v_and_b32_e32 v77, 0xffff0000, v71
	v_and_b32_e32 v71, 0xffff0000, v62
	v_fma_f32 v58, v11, v131, v68
	v_add_f32_e32 v58, v58, v69
	v_pk_mul_f32 v[68:69], v[108:109], v[70:71]
	v_mul_f32_e32 v58, v58, v75
	v_fma_f32 v62, v7, v131, v68
	v_add_f32_e32 v62, v62, v69
	v_mul_f32_e32 v127, v62, v72
	v_lshlrev_b32_e32 v72, 16, v59
	v_mov_b32_e32 v68, v128
	v_mov_b32_e32 v69, v72
	v_pk_mul_f32 v[68:69], v[100:101], v[68:69]
	v_cvt_pk_bf16_f32 v58, v73, v58
	v_lshlrev_b32_e32 v73, 16, v63
	v_fma_f32 v62, v12, v129, v68
	v_add_f32_e32 v62, v62, v69
	v_pk_mul_f32 v[68:69], v[110:111], v[72:73]
	v_mul_f32_e32 v76, v62, v76
	v_fma_f32 v62, v8, v129, v68
	v_add_f32_e32 v62, v62, v69
	v_and_b32_e32 v74, 0xffff0000, v59
	v_mul_f32_e32 v68, v62, v92
	v_and_b32_e32 v75, 0xffff0000, v63
	v_mov_b32_e32 v62, v78
	v_mov_b32_e32 v63, v74
	v_pk_mul_f32 v[62:63], v[20:21], v[62:63]
	v_and_b32_e32 v78, 0xffff0000, v60
	v_fma_f32 v59, v13, v79, v62
	v_add_f32_e32 v59, v59, v63
	v_pk_mul_f32 v[62:63], v[112:113], v[74:75]
	v_mul_f32_e32 v59, v59, v77
	v_fma_f32 v62, v9, v79, v62
	v_cvt_pk_bf16_f32 v59, v76, v59
	v_add_f32_e32 v62, v62, v63
	v_lshlrev_b32_e32 v76, 16, v60
	v_mul_f32_e32 v69, v62, v93
	v_mov_b32_e32 v62, v124
	v_mov_b32_e32 v63, v76
	v_pk_mul_f32 v[62:63], v[102:103], v[62:63]
	v_lshlrev_b32_e32 v77, 16, v64
	v_fma_f32 v62, v14, v125, v62
	v_add_f32_e32 v62, v62, v63
	v_mul_f32_e32 v82, v62, v82
	v_pk_mul_f32 v[62:63], v[114:115], v[76:77]
	v_and_b32_e32 v79, 0xffff0000, v64
	v_fma_f32 v62, v2, v125, v62
	v_add_f32_e32 v62, v62, v63
	v_mul_f32_e32 v92, v62, v94
	v_mov_b32_e32 v62, v88
	v_mov_b32_e32 v63, v78
	v_pk_mul_f32 v[62:63], v[22:23], v[62:63]
	v_and_b32_e32 v64, 0xffff0000, v61
	v_fma_f32 v60, v15, v89, v62
	v_add_f32_e32 v60, v60, v63
	v_pk_mul_f32 v[62:63], v[116:117], v[78:79]
	v_mul_f32_e32 v60, v60, v83
	v_fma_f32 v62, v3, v89, v62
	v_cvt_pk_bf16_f32 v60, v82, v60
	v_add_f32_e32 v62, v62, v63
	v_lshlrev_b32_e32 v82, 16, v61
	v_mul_f32_e32 v88, v62, v95
	v_mov_b32_e32 v62, v86
	v_mov_b32_e32 v63, v82
	v_pk_mul_f32 v[62:63], v[104:105], v[62:63]
	v_lshlrev_b32_e32 v83, 16, v65
	v_fma_f32 v62, v16, v87, v62
	v_add_f32_e32 v62, v62, v63
	v_mul_f32_e32 v86, v62, v90
	v_pk_mul_f32 v[62:63], v[118:119], v[82:83]
	v_and_b32_e32 v65, 0xffff0000, v65
	v_fma_f32 v62, v4, v87, v62
	v_add_f32_e32 v62, v62, v63
	v_mul_f32_e32 v87, v62, v96
	v_mov_b32_e32 v62, v80
	v_mov_b32_e32 v63, v64
	v_pk_mul_f32 v[62:63], v[24:25], v[62:63]
	s_waitcnt vmcnt(7)
	v_lshlrev_b32_e32 v89, 16, v52
	v_fma_f32 v61, v17, v81, v62
	v_add_f32_e32 v61, v61, v63
	v_mul_f32_e32 v61, v61, v91
	v_cvt_pk_bf16_f32 v61, v86, v61
	global_store_dwordx4 v[84:85], v[58:61], off
	v_lshlrev_b32_e32 v62, 16, v42
	v_and_b32_e32 v86, 0xffff0000, v57
	v_pk_mul_f32 v[58:59], v[120:121], v[64:65]
	s_waitcnt vmcnt(7)
; __device__ __forceinline__ float bf_lo(unsigned w) { return __uint_as_float(w << 16); }
; __device__ __forceinline__ float bf_hi(unsigned w) { return __uint_as_float(w & 0xffff0000u); }
; __device__ __forceinline__ unsigned pk2(float lo, float hi) { return pg8::cvt_pk_bf16(lo, hi); }
; __global__ void __launch_bounds__(NWAVES * 64, 2) trunk_fwd(Args args) {
;     ...
;                     for (int k = 0; k < 8; ++k) { const int i = i0 + k; const v4u bq = bqq[k], zq = zqq[k];
;                     const float bb[8] = {bf_lo(bq.x), bf_hi(bq.x), bf_lo(bq.y), bf_hi(bq.y), bf_lo(bq.z), bf_hi(bq.z), bf_lo(bq.w), bf_hi(bq.w)};
;                     const float z[8] = {bf_lo(zq.x), bf_hi(zq.x), bf_lo(zq.y), bf_hi(zq.y), bf_lo(zq.z), bf_hi(zq.z), bf_lo(zq.w), bf_hi(zq.w)};
;                     float y[8];
; #pragma unroll
;                     for (int e = 0; e < 8; ++e) { y[e] = bb[e] * (z2[e] * w0[e] + z1[e] * w1[e] + z[e] * w2[e]); z2[e] = z1[e]; z1[e] = z[e]; }
;                     v4u r; r.x = pk2(y[0], y[1]); r.y = pk2(y[2], y[3]); r.z = pk2(y[4], y[5]); r.w = pk2(y[6], y[7]);
;                     *(v4u*)(op + (size_t)i * 1024) = r; }
	v_lshlrev_b32_e32 v63, 16, v46
	v_fma_f32 v58, v5, v81, v58
	v_add_f32_e32 v58, v58, v59
	v_mul_f32_e32 v61, v58, v97
	v_cvt_pk_bf16_f32 v58, v126, v127
	v_cvt_pk_bf16_f32 v59, v68, v69
	v_cvt_pk_bf16_f32 v60, v92, v88
	v_cvt_pk_bf16_f32 v61, v87, v61
	global_store_dwordx4 v[84:85], v[58:61], off offset:2048
	v_lshlrev_b32_e32 v81, 16, v56
	v_and_b32_e32 v84, 0xffff0000, v56
	v_lshlrev_b32_e32 v85, 16, v57
	v_lshlrev_b32_e32 v56, 16, v50
	v_and_b32_e32 v57, 0xffff0000, v50
	v_lshlrev_b32_e32 v87, 16, v51
	v_and_b32_e32 v88, 0xffff0000, v51
	v_mov_b32_e32 v50, v66
	v_mov_b32_e32 v51, v62
	v_pk_mul_f32 v[50:51], v[98:99], v[50:51]
	v_lshlrev_b32_e32 v58, 16, v54
	v_fma_f32 v50, v10, v67, v50
	v_add_f32_e32 v50, v50, v51
	v_and_b32_e32 v90, 0xffff0000, v52
	v_mul_f32_e32 v52, v50, v58
	v_pk_mul_f32 v[50:51], v[106:107], v[62:63]
	v_and_b32_e32 v60, 0xffff0000, v42
	v_fma_f32 v50, v6, v67, v50
	v_add_f32_e32 v50, v50, v51
	v_mul_f32_e32 v69, v50, v56
	v_mov_b32_e32 v50, v70
	v_mov_b32_e32 v51, v60
	v_pk_mul_f32 v[50:51], v[18:19], v[50:51]
	v_and_b32_e32 v61, 0xffff0000, v46
	v_fma_f32 v42, v11, v71, v50
	v_add_f32_e32 v42, v42, v51
	v_pk_mul_f32 v[50:51], v[108:109], v[60:61]
	v_lshlrev_b32_e32 v58, 16, v43
	v_fma_f32 v46, v7, v71, v50
	v_add_f32_e32 v46, v46, v51
	v_mov_b32_e32 v50, v72
	v_mov_b32_e32 v51, v58
	v_pk_mul_f32 v[50:51], v[100:101], v[50:51]
	v_and_b32_e32 v54, 0xffff0000, v54
	v_mul_f32_e32 v70, v46, v57
	v_lshlrev_b32_e32 v59, 16, v47
	v_fma_f32 v46, v12, v73, v50
	v_lshlrev_b32_e32 v80, 16, v55
	v_mul_f32_e32 v42, v42, v54
	v_add_f32_e32 v46, v46, v51
	v_pk_mul_f32 v[50:51], v[110:111], v[58:59]
	v_cvt_pk_bf16_f32 v42, v52, v42
	v_mul_f32_e32 v52, v46, v80
	v_fma_f32 v46, v8, v73, v50
	v_add_f32_e32 v46, v46, v51
	v_and_b32_e32 v56, 0xffff0000, v43
	v_mul_f32_e32 v71, v46, v87
	v_and_b32_e32 v57, 0xffff0000, v47
	v_mov_b32_e32 v46, v74
	v_mov_b32_e32 v47, v56
	v_pk_mul_f32 v[46:47], v[20:21], v[46:47]
	v_lshlrev_b32_e32 v54, 16, v44
	v_fma_f32 v43, v13, v75, v46
	v_add_f32_e32 v43, v43, v47
	v_pk_mul_f32 v[46:47], v[112:113], v[56:57]
	v_and_b32_e32 v55, 0xffff0000, v55
	v_fma_f32 v46, v9, v75, v46
	v_add_f32_e32 v46, v46, v47
	v_mul_f32_e32 v72, v46, v88
	v_mov_b32_e32 v46, v76
	v_mov_b32_e32 v47, v54
	v_pk_mul_f32 v[46:47], v[102:103], v[46:47]
	v_mul_f32_e32 v43, v43, v55
	v_fma_f32 v46, v14, v77, v46
	v_lshlrev_b32_e32 v55, 16, v48
	v_add_f32_e32 v46, v46, v47
	v_mul_f32_e32 v50, v46, v81
	v_pk_mul_f32 v[46:47], v[114:115], v[54:55]
	v_cvt_pk_bf16_f32 v43, v52, v43
	v_and_b32_e32 v52, 0xffff0000, v44
	v_fma_f32 v46, v2, v77, v46
	v_add_f32_e32 v46, v46, v47
	v_mul_f32_e32 v73, v46, v89
	v_mov_b32_e32 v46, v78
	v_mov_b32_e32 v47, v52
	v_pk_mul_f32 v[46:47], v[22:23], v[46:47]
	v_lshlrev_b32_e32 v91, 16, v53
	v_and_b32_e32 v68, 0xffff0000, v53
	v_and_b32_e32 v53, 0xffff0000, v48
	v_fma_f32 v44, v15, v79, v46
	v_add_f32_e32 v44, v44, v47
	v_pk_mul_f32 v[46:47], v[116:117], v[52:53]
	v_mul_f32_e32 v44, v44, v84
	v_fma_f32 v46, v3, v79, v46
	v_cvt_pk_bf16_f32 v44, v50, v44
	v_add_f32_e32 v46, v46, v47
	v_lshlrev_b32_e32 v50, 16, v45
	v_mul_f32_e32 v74, v46, v90
	v_mov_b32_e32 v46, v82
	v_mov_b32_e32 v47, v50
	v_pk_mul_f32 v[46:47], v[104:105], v[46:47]
	v_lshlrev_b32_e32 v51, 16, v49
	v_fma_f32 v46, v16, v83, v46
	v_add_f32_e32 v46, v46, v47
	v_mul_f32_e32 v66, v46, v85
	v_pk_mul_f32 v[46:47], v[118:119], v[50:51]
	v_mov_b32_e32 v48, v64
	v_fma_f32 v46, v4, v83, v46
	v_add_f32_e32 v46, v46, v47
	v_mul_f32_e32 v75, v46, v91
	v_and_b32_e32 v46, 0xffff0000, v45
	v_and_b32_e32 v47, 0xffff0000, v49
	v_mov_b32_e32 v49, v46
	v_pk_mul_f32 v[48:49], v[24:25], v[48:49]
	s_waitcnt vmcnt(6)
	v_lshlrev_b32_e32 v82, 16, v26
	v_fma_f32 v45, v17, v65, v48
	v_add_f32_e32 v45, v45, v49
	v_mul_f32_e32 v45, v45, v86
	v_cvt_pk_bf16_f32 v45, v66, v45
	v_add_co_u32_e32 v66, vcc, s27, v122
	s_mov_b32 s27, 0x14a03000
	s_nop 0
	v_addc_co_u32_e32 v67, vcc, 0, v123, vcc
	v_add_co_u32_e32 v48, vcc, s27, v122
	s_waitcnt vmcnt(5)
	v_lshlrev_b32_e32 v64, 16, v34
	v_addc_co_u32_e32 v49, vcc, 0, v123, vcc
	global_store_dwordx4 v[48:49], v[42:45], off offset:-4096
	s_waitcnt vmcnt(5)
; __global__ void __launch_bounds__(NWAVES * 64, 2) trunk_fwd(Args args) {
;     ...
;         else if (kind == K_ATTN) {
;             const LAS float* tab = (const LAS float*)(L + TAB_OFF); int cur_h = -1;
;             for (int item = bid; item < 256; item += G) {
;                 const int it2 = (item & 7) * 32 + (item >> 3), b = it2 >> 4, h = (it2 >> 2) & 3, sq = it2 & 3;
;                 if (h != cur_h) { __syncthreads(); { LAS float* tw = (LAS float*)(L + TAB_OFF); const float t0v = TAB[h * TABN + tid]; const float t1v = TAB[h * TABN + (tid < TABN - 512 ? tid + 512 : tid)]; tw[tid] = t0v; if (tid < TABN - 512) tw[tid + 512] = t1v; } cur_h = h; asm volatile("s_waitcnt vmcnt(0) lgkmcnt(0)" ::: "memory"); __syncthreads(); }
;                 for (int qi = 0; qi < 4; ++qi) {
;                     const int qb = qi == 0 ? 15 - sq : qi == 1 ? 8 + sq : qi == 2 ? 7 - sq : sq;
;                     for (int vh = 0; vh < 4; ++vh) { const int mp = vh >> 1, j = vh & 1;
;     ...
;                         attn_body::attn_unit<8>(b, qb, (const attn_body::bf16*)(BIG + h * 128 + mp * 64), (const attn_body::bf16*)(BIG + 512 + h * 128 + mp * 64), (const attn_body::bf16*)(BIG + 1024 + h * 128 + j * 64),
;                                                 (attn_body::bf16*)(ORAW + mp * 512 + h * 128 + j * 64), tab, (char*)lds);
;     ...
;                         asm volatile("s_waitcnt vmcnt(0)" ::: "memory");
;                     }
;                     __syncthreads();
;                     { int lane_ = threadIdx.x & 63; asm volatile("" : "+v"(lane_));
;     ...
;                     for (int k = 0; k < 8; ++k) { const int i = i0 + k; const v4u bq = bqq[k], zq = zqq[k];
;                     const float bb[8] = {bf_lo(bq.x), bf_hi(bq.x), bf_lo(bq.y), bf_hi(bq.y), bf_lo(bq.z), bf_hi(bq.z), bf_lo(bq.w), bf_hi(bq.w)};
;                     const float z[8] = {bf_lo(zq.x), bf_hi(zq.x), bf_lo(zq.y), bf_hi(zq.y), bf_lo(zq.z), bf_hi(zq.z), bf_lo(zq.w), bf_hi(zq.w)};
;                     float y[8];
; #pragma unroll
;                     for (int e = 0; e < 8; ++e) { y[e] = bb[e] * (z2[e] * w0[e] + z1[e] * w1[e] + z[e] * w2[e]); z2[e] = z1[e]; z1[e] = z[e]; }
;                     v4u r; r.x = pk2(y[0], y[1]); r.y = pk2(y[2], y[3]); r.z = pk2(y[4], y[5]); r.w = pk2(y[6], y[7]);
;                     *(v4u*)(op + (size_t)i * 1024) = r; }
;                 }
;             }
	v_lshlrev_b32_e32 v83, 16, v30
	v_and_b32_e32 v84, 0xffff0000, v26
	v_pk_mul_f32 v[42:43], v[120:121], v[46:47]
	v_and_b32_e32 v85, 0xffff0000, v30
	v_fma_f32 v42, v5, v65, v42
	v_add_f32_e32 v42, v42, v43
	v_mul_f32_e32 v45, v42, v68
	v_cvt_pk_bf16_f32 v42, v69, v70
	v_cvt_pk_bf16_f32 v43, v71, v72
	v_cvt_pk_bf16_f32 v44, v73, v74
	v_cvt_pk_bf16_f32 v45, v75, v45
	global_store_dwordx4 v[66:67], v[42:45], off offset:2048
	v_and_b32_e32 v65, 0xffff0000, v34
	v_lshlrev_b32_e32 v66, 16, v35
	v_and_b32_e32 v67, 0xffff0000, v35
	v_mov_b32_e32 v34, v62
	v_mov_b32_e32 v35, v82
	v_pk_mul_f32 v[34:35], v[98:99], v[34:35]
	v_lshlrev_b32_e32 v42, 16, v38
	v_fma_f32 v34, v10, v63, v34
	v_add_f32_e32 v34, v34, v35
	v_mul_f32_e32 v42, v34, v42
	v_pk_mul_f32 v[34:35], v[106:107], v[82:83]
	v_lshlrev_b32_e32 v86, 16, v27
	v_fma_f32 v34, v6, v63, v34
	v_add_f32_e32 v34, v34, v35
	v_mul_f32_e32 v62, v34, v64
	v_mov_b32_e32 v34, v60
	v_mov_b32_e32 v35, v84
	v_pk_mul_f32 v[34:35], v[18:19], v[34:35]
	v_and_b32_e32 v38, 0xffff0000, v38
	v_fma_f32 v26, v11, v61, v34
	v_add_f32_e32 v26, v26, v35
	v_pk_mul_f32 v[34:35], v[108:109], v[84:85]
	v_mul_f32_e32 v26, v26, v38
	v_fma_f32 v30, v7, v61, v34
	v_add_f32_e32 v30, v30, v35
	v_mov_b32_e32 v34, v58
	v_mov_b32_e32 v35, v86
	v_pk_mul_f32 v[34:35], v[100:101], v[34:35]
	v_mul_f32_e32 v38, v30, v65
	v_lshlrev_b32_e32 v87, 16, v31
	v_fma_f32 v30, v12, v59, v34
	v_lshlrev_b32_e32 v43, 16, v39
	v_add_f32_e32 v30, v30, v35
	v_pk_mul_f32 v[34:35], v[110:111], v[86:87]
	v_cvt_pk_bf16_f32 v26, v42, v26
	v_mul_f32_e32 v42, v30, v43
	v_fma_f32 v30, v8, v59, v34
	v_add_f32_e32 v30, v30, v35
	v_and_b32_e32 v88, 0xffff0000, v27
	v_mul_f32_e32 v34, v30, v66
	v_and_b32_e32 v89, 0xffff0000, v31
	v_mov_b32_e32 v30, v56
	v_mov_b32_e32 v31, v88
	v_pk_mul_f32 v[30:31], v[20:21], v[30:31]
	v_lshlrev_b32_e32 v90, 16, v28
	v_fma_f32 v27, v13, v57, v30
	v_add_f32_e32 v27, v27, v31
	v_pk_mul_f32 v[30:31], v[112:113], v[88:89]
	v_and_b32_e32 v39, 0xffff0000, v39
	v_fma_f32 v30, v9, v57, v30
	v_add_f32_e32 v30, v30, v31
	v_mul_f32_e32 v35, v30, v67
	v_mov_b32_e32 v30, v54
	v_mov_b32_e32 v31, v90
	v_pk_mul_f32 v[30:31], v[102:103], v[30:31]
	v_lshlrev_b32_e32 v44, 16, v40
	v_fma_f32 v30, v14, v55, v30
	v_lshlrev_b32_e32 v91, 16, v32
	v_add_f32_e32 v30, v30, v31
	v_mul_f32_e32 v27, v27, v39
	v_mul_f32_e32 v39, v30, v44
	v_pk_mul_f32 v[30:31], v[114:115], v[90:91]
	v_lshlrev_b32_e32 v68, 16, v36
	v_fma_f32 v30, v2, v55, v30
	v_add_f32_e32 v30, v30, v31
	v_and_b32_e32 v92, 0xffff0000, v28
	v_cvt_pk_bf16_f32 v27, v42, v27
	v_mul_f32_e32 v42, v30, v68
	v_mov_b32_e32 v30, v52
	v_mov_b32_e32 v31, v92
	v_pk_mul_f32 v[30:31], v[22:23], v[30:31]
	v_and_b32_e32 v93, 0xffff0000, v32
	v_fma_f32 v28, v15, v53, v30
	v_add_f32_e32 v28, v28, v31
	v_pk_mul_f32 v[30:31], v[116:117], v[92:93]
	v_and_b32_e32 v36, 0xffff0000, v36
	v_fma_f32 v30, v3, v53, v30
	v_add_f32_e32 v30, v30, v31
	v_lshlrev_b32_e32 v94, 16, v29
	v_mul_f32_e32 v32, v30, v36
	v_mov_b32_e32 v30, v50
	v_mov_b32_e32 v31, v94
	v_pk_mul_f32 v[30:31], v[104:105], v[30:31]
	v_lshlrev_b32_e32 v45, 16, v41
	v_fma_f32 v30, v16, v51, v30
	v_lshlrev_b32_e32 v95, 16, v33
	v_add_f32_e32 v30, v30, v31
	v_mul_f32_e32 v36, v30, v45
	v_pk_mul_f32 v[30:31], v[118:119], v[94:95]
	v_and_b32_e32 v40, 0xffff0000, v40
	v_fma_f32 v30, v4, v51, v30
	v_lshlrev_b32_e32 v69, 16, v37
	v_mul_f32_e32 v28, v28, v40
	v_add_f32_e32 v30, v30, v31
	v_and_b32_e32 v96, 0xffff0000, v29
	v_cvt_pk_bf16_f32 v28, v39, v28
	v_mul_f32_e32 v39, v30, v69
	v_mov_b32_e32 v30, v46
	v_mov_b32_e32 v31, v96
	v_pk_mul_f32 v[30:31], v[24:25], v[30:31]
	v_and_b32_e32 v41, 0xffff0000, v41
	v_fma_f32 v29, v17, v47, v30
	v_add_f32_e32 v29, v29, v31
	v_and_b32_e32 v97, 0xffff0000, v33
	v_mul_f32_e32 v29, v29, v41
	v_cvt_pk_bf16_f32 v29, v36, v29
	global_store_dwordx4 v[48:49], v[26:29], off
	v_and_b32_e32 v37, 0xffff0000, v37
	v_mov_b32_e32 v130, v82
	v_pk_mul_f32 v[26:27], v[120:121], v[96:97]
	v_mov_b32_e32 v128, v84
	v_fma_f32 v26, v5, v47, v26
	v_add_f32_e32 v26, v26, v27
	v_mul_f32_e32 v29, v26, v37
	v_mov_b32_e32 v126, v86
	v_mov_b32_e32 v124, v88
	v_mov_b32_e32 v88, v90
	v_mov_b32_e32 v86, v92
	v_mov_b32_e32 v84, v94
	v_mov_b32_e32 v82, v96
	v_cvt_pk_bf16_f32 v26, v62, v38
	v_cvt_pk_bf16_f32 v27, v34, v35
	v_cvt_pk_bf16_f32 v28, v42, v32
	v_cvt_pk_bf16_f32 v29, v39, v29
	global_store_dwordx4 v[48:49], v[26:29], off offset:2048
	s_cbranch_scc0 .LBB0_350
	s_addk_i32 s20, 0x100
	s_add_i32 s3, s3, s12
	s_add_i32 s14, s14, s15
	s_bitcmp0_b32 s20, 8
	v_readlane_b32 s27, v255, 26
	v_readlane_b32 s26, v255, 27
	s_cbranch_scc0 .LBB0_346
.LBB0_352:
	s_andn2_b64 vcc, exec, s[70:71]
	s_cbranch_vccnz .LBB0_449
	v_readlane_b32 s3, v255, 15
	s_cmp_gt_i32 s3, 1
	s_mov_b64 s[4:5], -1
	v_readlane_b32 s66, v255, 18
	v_readlane_b32 s67, v255, 19
	s_cbranch_scc0 .LBB0_591
	v_readlane_b32 s3, v255, 15
	s_cmp_eq_u32 s3, 2
	s_mov_b64 s[68:69], -1
	s_cbranch_scc0 .LBB0_590
	s_cmpk_gt_i32 s48, 0xff
	s_cbranch_scc1 .LBB0_612
	s_add_u32 s2, s18, 0x100000
	s_addc_u32 s3, s19, 0
	v_writelane_b32 v255, s2, 28
	s_and_b32 s4, s48, 7
	s_mul_i32 s2, s4, 0x3000000
	s_lshl_b32 s4, s4, 25
	s_add_u32 s2, s2, 0x1ea00000
	s_add_u32 s70, s18, s2
	s_addc_u32 s71, s19, 0
	v_writelane_b32 v255, s3, 29
	s_movk_i32 s3, 0xc0
	v_cmp_gt_i32_e64 s[2:3], s3, v250
	s_add_u32 s5, s4, 0x1ca00400
	s_add_u32 s1, s18, s5
	v_add_u32_e32 v0, 0x200, v250
	v_writelane_b32 v255, s2, 30
	v_mov_b32_e32 v2, 0x3f4ccccd
	v_lshl_add_u32 v218, v250, 2, 0
	v_writelane_b32 v255, s3, 31
	v_writelane_b32 v255, s1, 32
	s_addc_u32 s1, s19, 0
	v_writelane_b32 v255, s1, 33
	s_add_u32 s5, s4, 0x1ca00800
	s_add_u32 s1, s18, s5
	v_writelane_b32 v255, s1, 34
	s_addc_u32 s1, s19, 0
	v_writelane_b32 v255, s1, 35
	v_cndmask_b32_e64 v217, v250, v0, s[2:3]
	v_readlane_b32 s2, v255, 24
	s_mov_b32 s6, s2
	s_ashr_i32 s7, s2, 31
	v_readlane_b32 s3, v255, 25
	s_lshl_b64 s[4:5], s[6:7], 2
	s_add_u32 s3, s18, s4
	s_addc_u32 s4, s19, s5
	s_add_u32 s72, s3, 0x104000
	s_addc_u32 s73, s4, 0
	v_readlane_b32 s2, v255, 16
	v_readlane_b32 s3, v255, 17
	s_cmp_lt_u32 s2, 2
	s_mov_b32 s2, s6
	v_writelane_b32 v255, s2, 24
	s_cselect_b64 vcc, -1, 0
	s_lshl_b32 s6, s6, 7
	v_writelane_b32 v255, s3, 25
	v_mov_b32_e32 v0, 0x3f077f5a
	v_readlane_b32 s1, v255, 20
	s_ashr_i32 s7, s6, 31
	s_lshl_b32 s67, s1, 5
	s_mov_b32 s1, -1
	v_cndmask_b32_e32 v219, v0, v2, vcc
	s_ashr_i32 s4, s67, 31
	v_writelane_b32 v255, s1, 36
	s_lshl_b64 s[74:75], s[6:7], 2
	s_mov_b32 s5, s48
	s_branch .LBB0_358

; __global__ void __launch_bounds__(NWAVES * 64, 2) trunk_fwd(Args args) {
;     ...
;             { const int w = 2 << (lane >> 4);
;               for (int task = gw; task < M / 32; task += NGW) {
;                 const int row0 = task * 32, t0 = row0 & (SEQ - 1);
;                 const bf16* up = BIG + (size_t)row0 * 2048 + 1536 + lane * 8; bf16* op = MIX + (size_t)row0 * 1024 + 512 + lane * 8;
.LBB0_612:
	v_readlane_b32 s42, v255, 22
	s_cmpk_gt_i32 s60, 0x7ff
	v_readlane_b32 s66, v255, 18
	v_readlane_b32 s28, v255, 21
	v_readlane_b32 s43, v255, 23
	v_readlane_b32 s67, v255, 19
	s_cbranch_scc1 .LBB0_630
	v_lshrrev_b32_e32 v0, 4, v216
	s_waitcnt vmcnt(0)
	v_lshlrev_b32_e64 v52, v0, 2
	v_lshlrev_b32_e32 v0, 4, v216
	s_waitcnt lgkmcnt(0)
	v_lshl_add_u64 v[2:3], s[18:19], 0, v[0:1]
	s_mov_b64 s[4:5], 0x1c9ffc00
	v_lshl_add_u64 v[26:27], v[2:3], 0, s[4:5]
	v_readlane_b32 s4, v255, 20
	s_and_b32 s3, s48, 7
	s_lshl_b32 s3, s3, 8
	v_mov_b64_e32 v[2:3], s[18:19]
	s_movk_i32 s5, 0xf000
	s_add_i32 s4, s3, s4
	s_lshr_b32 s3, s48, 3
	s_lshl_b32 s3, s3, 3
	s_add_i32 s4, s4, s3
	s_lshl_b32 s3, s0, 8
	v_mad_i64_i32 v[28:29], s[6:7], v52, s5, v[2:3]
	s_mov_b32 s12, s4
	s_lshl_b32 s4, s4, 5
	s_branch .LBB0_615

; __device__ __forceinline__ float bf_lo(unsigned w) { return __uint_as_float(w << 16); }
; __device__ __forceinline__ float bf_hi(unsigned w) { return __uint_as_float(w & 0xffff0000u); }
; __global__ void __launch_bounds__(NWAVES * 64, 2) trunk_fwd(Args args) {
;     ...
;               for (int task = gw; task < M / 32; task += NGW) {
;                 const int row0 = task * 32, t0 = row0 & (SEQ - 1);
;                 const bf16* up = BIG + (size_t)row0 * 2048 + 1536 + lane * 8; bf16* op = MIX + (size_t)row0 * 1024 + 512 + lane * 8;
;                 float sum[8];
; #pragma unroll
;                 for (int e = 0; e < 8; ++e) sum[e] = 0.f;
;                 if (t0 > 0) for (int jj = 1; jj <= w; ++jj) {   const v4u q = *(const v4u*)(up - (size_t)jj * 2048);
;                     sum[0] += bf_lo(q.x); sum[1] += bf_hi(q.x); sum[2] += bf_lo(q.y); sum[3] += bf_hi(q.y); sum[4] += bf_lo(q.z); sum[5] += bf_hi(q.z); sum[6] += bf_lo(q.w); sum[7] += bf_hi(q.w); }
.LBB0_615:
	s_ashr_i32 s5, s4, 31
	s_lshl_b32 s6, s12, 5
	s_lshl_b64 s[68:69], s[4:5], 12
	s_and_b32 s7, s48, 7
	s_lshl_b32 s7, s7, 25
	s_add_u32 s68, s68, s7
	s_addc_u32 s69, s69, 0
	s_and_b32 s6, s6, 0xfe0
	s_cmp_eq_u32 s6, 0
	s_cbranch_scc1 .LBB0_619
	v_mov_b32_e32 v32, 0
	v_lshl_add_u64 v[2:3], v[26:27], 0, s[68:69]
	s_mov_b64 s[6:7], 0
	v_mov_b32_e32 v4, v52
	v_mov_b32_e32 v33, v32
	v_mov_b32_e32 v38, v32
	v_mov_b32_e32 v39, v32
	v_mov_b32_e32 v36, v32
	v_mov_b32_e32 v37, v32
	v_mov_b32_e32 v34, v32
	v_mov_b32_e32 v35, v32

; __device__ __forceinline__ unsigned xb_ld(unsigned* p)              { return __hip_atomic_load(p, __ATOMIC_RELAXED, __HIP_MEMORY_SCOPE_AGENT); }
; __device__ __forceinline__ unsigned xb_add(unsigned* p, unsigned v) { return __hip_atomic_fetch_add(p, v, __ATOMIC_RELAXED, __HIP_MEMORY_SCOPE_AGENT); }
; #define XB_SPIN(cond, bar) do { unsigned _sp = 0; while (cond) { __builtin_amdgcn_s_sleep(1); \
;     if ((++_sp & 255u) == 0u) { if (xb_ld(&(bar)[XB_TMO])) break; if (_sp > XB_SPIN_CAP) { atomicAdd(&(bar)[XB_TMO], 1u); break; } } } } while (0)
; __device__ __forceinline__ void xcd_barrier(const XcdBarrier& b) {
;     asm volatile("s_waitcnt vmcnt(0)" ::: "memory");
;     __syncthreads();
;     if (threadIdx.x == 0) {
;         unsigned* bar = b.bar;
;         __builtin_amdgcn_s_waitcnt(0);
;         unsigned nloc = b.st[0], nx = b.st[1];
;         if (nloc == 0u) { xcd_barrier_complete(bar, b.x, nloc, nx); b.st[0] = nloc; b.st[1] = nx; }
;         const unsigned old = xb_add(&bar[XB_XSUB(b.x)], 1u);
;         const unsigned gen = old / nloc;
;         if (old + 1u == (gen + 1u) * nloc) {
;             __builtin_amdgcn_fence(__ATOMIC_RELEASE, "agent");
;             asm volatile("s_waitcnt vmcnt(0)" ::: "memory");
;             const unsigned og = xb_add(&bar[XB_TOP], 1u);
;             const unsigned tg = og / nx;
;             if (og + 1u == (tg + 1u) * nx) xb_add(&bar[XB_TOPGEN], 1u);
;             else XB_SPIN(xb_ld(&bar[XB_TOPGEN]) == tg, bar);
;             __builtin_amdgcn_fence(__ATOMIC_ACQUIRE, "agent");
;             xb_add(&bar[XB_XGEN(b.x)], 1u);
.LBB0_652:
	s_andn2_saveexec_b64 s[8:9], s[8:9]
	s_cbranch_execz .LBB0_169
	s_mov_b64 s[8:9], exec
	s_waitcnt lgkmcnt(0)
	v_readlane_b32 s0, v255, 9
	s_sub_u32 s0, s0, 3
	s_cmp_lt_u32 s0, 26
	s_cbranch_scc1 .Lxb_local
	buffer_wbl2 sc1
	s_waitcnt lgkmcnt(0)
	s_waitcnt vmcnt(0)
	v_mbcnt_lo_u32_b32 v2, s8, 0
	v_mbcnt_hi_u32_b32 v2, s9, v2
	v_cmp_eq_u32_e32 vcc, 0, v2
	s_and_saveexec_b64 s[16:17], vcc
	s_cbranch_execz .LBB0_655
	s_bcnt1_i32_b64 s0, s[8:9]
	v_mov_b32_e32 v3, s0
	v_mov_b32_e32 v4, 0x3000
	global_atomic_add v3, v4, v3, s[18:19] offset:1024 sc0

; __device__ __forceinline__ unsigned xb_ld(unsigned* p)              { return __hip_atomic_load(p, __ATOMIC_RELAXED, __HIP_MEMORY_SCOPE_AGENT); }
; __device__ __forceinline__ unsigned xb_add(unsigned* p, unsigned v) { return __hip_atomic_fetch_add(p, v, __ATOMIC_RELAXED, __HIP_MEMORY_SCOPE_AGENT); }
; #define XB_SPIN(cond, bar) do { unsigned _sp = 0; while (cond) { __builtin_amdgcn_s_sleep(1); \
;     if ((++_sp & 255u) == 0u) { if (xb_ld(&(bar)[XB_TMO])) break; if (_sp > XB_SPIN_CAP) { atomicAdd(&(bar)[XB_TMO], 1u); break; } } } } while (0)
; __device__ __forceinline__ void xcd_barrier(const XcdBarrier& b) {
;     asm volatile("s_waitcnt vmcnt(0)" ::: "memory");
;     __syncthreads();
;     if (threadIdx.x == 0) {
;         unsigned* bar = b.bar;
;         __builtin_amdgcn_s_waitcnt(0);
;         unsigned nloc = b.st[0], nx = b.st[1];
;         if (nloc == 0u) { xcd_barrier_complete(bar, b.x, nloc, nx); b.st[0] = nloc; b.st[1] = nx; }
;         const unsigned old = xb_add(&bar[XB_XSUB(b.x)], 1u);
;         const unsigned gen = old / nloc;
;         if (old + 1u == (gen + 1u) * nloc) {
;             __builtin_amdgcn_fence(__ATOMIC_RELEASE, "agent");
;             asm volatile("s_waitcnt vmcnt(0)" ::: "memory");
;             const unsigned og = xb_add(&bar[XB_TOP], 1u);
;             const unsigned tg = og / nx;
;             if (og + 1u == (tg + 1u) * nx) xb_add(&bar[XB_TOPGEN], 1u);
;             else XB_SPIN(xb_ld(&bar[XB_TOPGEN]) == tg, bar);
;             __builtin_amdgcn_fence(__ATOMIC_ACQUIRE, "agent");
;             xb_add(&bar[XB_XGEN(b.x)], 1u);
;             asm volatile("s_waitcnt vmcnt(0)" ::: "memory");
;         } else {
;             XB_SPIN(xb_ld(&bar[XB_XGEN(b.x)]) == gen, bar);
;             __builtin_amdgcn_fence(__ATOMIC_ACQUIRE, "agent");
;             asm volatile("s_waitcnt vmcnt(0)" ::: "memory");
;         }
;     }
;     __syncthreads();
; }
.Lxb_local:
	s_mov_b64 s[8:9], exec
	v_mbcnt_lo_u32_b32 v0, s8, 0
	v_mbcnt_hi_u32_b32 v0, s9, v0
	v_cmp_eq_u32_e32 vcc, 0, v0
	s_waitcnt vmcnt(0)
	buffer_inv sc1
	s_and_saveexec_b64 s[16:17], vcc
	s_cbranch_execz .LBB0_168
	s_bcnt1_i32_b64 s0, s[8:9]
	v_mov_b32_e32 v0, s0
	global_atomic_add v247, v0, s[6:7] offset:1024
	s_branch .LBB0_168
